# top-k scoring first-chunk key-tile loads issued in permuted lane order through twin pointers, un-permuted with ds_bpermute at the loop head, on top of v025
# baseline (speedup 1.0000x reference)
; DEVI void topk_unit(const Params& p, const int u, unsigned char* smem) {
;     int tid = threadIdx.x; asm volatile("" : "+v"(tid));
;     const int lane = tid & 63, w = tid >> 6, l15 = lane & 15, g = lane >> 4;
;     int wq = w * 16 + 4 * g; asm volatile("" : "+v"(wq));
;     int wl = w * 16 + l15; asm volatile("" : "+v"(wl));
;     unsigned char* qs = smem;
;     unsigned* KL = (unsigned*)(smem + TK_QS);
;     const bool prompt = u < 2048;
;     int b, tok0, lim;
;     if (prompt) { b = u & 7; const int qt = u >> 3; tok0 = b * 4096 + qt * 16; lim = (((qt * 16) >> 6) + 1) * 64; }
;     else { const int v = u - 2048; b = v >> 1; tok0 = NTP + b * 32 + (v & 1) * 16; lim = 2080; }
;     const int ni = (lim + 127) >> 7;
;     const int npair = (ni + 1) >> 1;
.LBB0_412:
	v_mov_b32_e32 v25, v203
	s_cmpk_gt_i32 s93, 0x7ff
	v_ashrrev_i32_e32 v171, 6, v25
	v_and_b32_e32 v28, 15, v25
	v_bfe_u32 v8, v25, 4, 2
	v_lshlrev_b32_e32 v0, 4, v171
	v_and_b32_e32 v253, 63, v25
	v_and_b32_e32 v254, 3, v253
	v_lshrrev_b32_e32 v250, 4, v253
	v_bfe_u32 v255, v253, 2, 2
	v_lshlrev_b32_e32 v253, 4, v255
	v_lshl_add_u32 v253, v254, 2, v253
	v_add_u32_e32 v253, v253, v250
	v_lshlrev_b32_e32 v253, 2, v253
	v_lshl_add_u32 v255, v250, 2, v255
	v_mov_b32_e32 v251, 0
	s_cselect_b64 s[4:5], -1, 0
	v_lshl_or_b32 v175, v8, 2, v0
	v_or_b32_e32 v168, v0, v28
	v_or_b32_e32 v252, v0, v255
	s_and_b64 vcc, exec, s[4:5]
	s_mov_b64 s[0:1], -1
	s_cbranch_vccz .LBB0_414
	s_add_i32 s0, s93, 0xfffff800
	s_lshr_b32 s94, s0, 1
	s_lshl_b32 s1, s93, 4
	s_lshl_b32 s0, s94, 5
	s_and_b32 s1, s1, 16
	s_or_b32 s0, s0, s1
	s_add_i32 s90, s0, 0x8000
	s_mov_b64 s[0:1], 0

; DEVI void topk_unit(const Params& p, const int u, unsigned char* smem) {
;     ...
;     const bf16_t* QI = (const bf16_t*)(p.ws + W_QI);
; #pragma unroll
;     for (int j = 0; j < 2; ++j) {
;         const int id = tid + 512 * j, row = id >> 6, c = id & 63;
;         *(u32x4*)(qs + row * 1040 + c * 16) = *(const u32x4*)(QI + (size_t)(tok0 + row) * 512 + c * 8);
;     }
;     float wv[8];
;     {
;         const float* WI = (const float*)(p.ws + W_WI) + (size_t)(tok0 + l15) * 8;
;         const f32x4 a = *(const f32x4*)WI, c = *(const f32x4*)(WI + 4);
;         wv[0] = a[0] * 0.125f; wv[1] = a[1] * 0.125f; wv[2] = a[2] * 0.125f; wv[3] = a[3] * 0.125f;
;         wv[4] = c[0] * 0.125f; wv[5] = c[1] * 0.125f; wv[6] = c[2] * 0.125f; wv[7] = c[3] * 0.125f;
;     }
;     const bf16_t* KIP = (const bf16_t*)(p.ws + W_KIP) + (size_t)b * 4096 * 64 + 8 * g;
;     const float* CIK = p.c_ik + (size_t)b * 2048 * 64 + 8 * g;
;     const float* NIK = p.out + O_IKS + (size_t)b * 32 * 64 + 8 * g;
;     ...
;     u32x4 ka0, ka1, kb0, kb1, na0, na1, nb0, nb1;
;     TK_LOADK(ka0, ka1, 0); TK_LOADK(kb0, kb1, 1);
.LBB0_416:
	v_add_u32_e32 v4, 0x200, v25
	v_ashrrev_i32_e32 v9, 6, v4
	v_and_b32_e32 v172, 63, v25
	v_add_u32_e32 v2, s90, v171
	v_add_u32_e32 v4, s90, v9
	v_lshlrev_b32_e32 v32, 4, v172
	v_ashrrev_i32_e32 v3, 31, v2
	v_ashrrev_i32_e32 v5, 31, v4
	v_lshl_add_u64 v[0:1], s[84:85], 0, v[32:33]
	v_lshlrev_b64 v[2:3], 10, v[2:3]
	v_lshlrev_b64 v[4:5], 10, v[4:5]
	v_lshl_add_u64 v[2:3], v[0:1], 0, v[2:3]
	v_lshl_add_u64 v[0:1], v[0:1], 0, v[4:5]
	global_load_dwordx4 v[10:13], v[2:3], off
	global_load_dwordx4 v[34:37], v[0:1], off
	v_add_u32_e32 v0, s90, v28
	v_ashrrev_i32_e32 v1, 31, v0
	v_lshlrev_b64 v[0:1], 5, v[0:1]
	v_lshl_add_u64 v[0:1], s[74:75], 0, v[0:1]
	global_load_dwordx4 v[16:19], v[0:1], off offset:16
	global_load_dwordx4 v[20:23], v[0:1], off
	s_lshl_b64 s[8:9], s[94:95], 19
	v_readlane_b32 s0, v234, 43
	s_add_u32 s0, s0, s8
	v_readlane_b32 s1, v234, 59
	v_readlane_b32 s36, v234, 2
	v_add_u32_e32 v24, 0, v32
	s_addc_u32 s1, s1, s9
	v_readlane_b32 s44, v234, 10
	v_mad_u64_u32 v[14:15], s[10:11], v171, s33, v[24:25]
	v_mad_u64_u32 v[26:27], s[10:11], v9, s33, v[24:25]
	v_readlane_b32 s45, v234, 11
	s_add_u32 s8, s44, s8
	v_lshlrev_b32_e32 v32, 5, v8
	v_lshlrev_b32_e32 v250, 5, v254
	s_addc_u32 s9, s45, s9
	s_lshl_b64 s[10:11], s[94:95], 13
	v_readlane_b32 s2, v234, 57
	v_lshl_add_u64 v[146:147], s[8:9], 0, v[32:33]
	v_lshl_add_u64 v[240:241], s[8:9], 0, v[250:251]
	s_add_u32 s8, s2, s10
	v_readlane_b32 s2, v234, 55
	s_addc_u32 s9, s2, s11
	s_mov_b64 s[6:7], -1
	s_and_b64 vcc, exec, s[4:5]
	v_lshl_add_u64 v[148:149], s[8:9], 0, v[32:33]
	v_lshl_add_u64 v[242:243], s[8:9], 0, v[250:251]
	v_readlane_b32 s37, v234, 3
	v_readlane_b32 s38, v234, 4
	v_readlane_b32 s39, v234, 5
	v_readlane_b32 s40, v234, 6
	v_readlane_b32 s41, v234, 7
	v_readlane_b32 s42, v234, 8
	v_readlane_b32 s43, v234, 9
	v_readlane_b32 s46, v234, 12
	v_readlane_b32 s47, v234, 13
	v_readlane_b32 s48, v234, 14
	v_readlane_b32 s49, v234, 15
	v_readlane_b32 s50, v234, 16
	v_readlane_b32 s51, v234, 17
	s_waitcnt vmcnt(3)
	ds_write_b128 v14, v[10:13]
	s_waitcnt vmcnt(2)
	ds_write_b128 v26, v[34:37]
	s_cbranch_vccz .LBB0_418
	v_min_i32_e32 v0, 0x81f, v252
	v_add_u32_e32 v2, 0xfffff800, v0
	v_ashrrev_i32_e32 v1, 31, v0
	v_cmp_gt_i32_e32 vcc, s96, v252
	s_nop 1
	v_cndmask_b32_e32 v1, 0, v1, vcc
	v_cndmask_b32_e32 v0, v2, v0, vcc
	v_cndmask_b32_e32 v3, v243, v241, vcc
	v_cndmask_b32_e32 v2, v242, v240, vcc
	v_lshlrev_b64 v[0:1], 8, v[0:1]
	v_lshl_add_u64 v[14:15], v[2:3], 0, v[0:1]
	global_load_dwordx4 v[0:3], v[14:15], off
	global_load_dwordx4 v[4:7], v[14:15], off offset:16
	global_load_dwordx4 v[10:13], v[14:15], off offset:128
	global_load_dwordx4 v[34:37], v[14:15], off offset:144
	s_waitcnt vmcnt(3)
	v_cvt_pk_bf16_f32 v0, v0, v1
	v_cvt_pk_bf16_f32 v1, v2, v3
	s_waitcnt vmcnt(2)
	v_cvt_pk_bf16_f32 v2, v4, v5
	v_cvt_pk_bf16_f32 v3, v6, v7
	s_waitcnt vmcnt(1)
	v_cvt_pk_bf16_f32 v4, v10, v11
	v_cvt_pk_bf16_f32 v5, v12, v13
	s_waitcnt vmcnt(0)
	v_cvt_pk_bf16_f32 v6, v34, v35
	v_cvt_pk_bf16_f32 v7, v36, v37
	v_lshlrev_b32_e32 v32, 4, v8
	v_lshlrev_b32_e32 v250, 4, v254
	v_lshl_add_u64 v[150:151], s[0:1], 0, v[32:33]
	v_lshl_add_u64 v[244:245], s[0:1], 0, v[250:251]
	s_cbranch_execnz .LBB0_420
	s_branch .LBB0_419
.LBB0_418:
	v_lshlrev_b32_e32 v32, 4, v8
	v_lshlrev_b32_e32 v250, 4, v254
	s_andn2_b64 vcc, exec, s[6:7]
	v_lshl_add_u64 v[150:151], s[0:1], 0, v[32:33]
	v_lshl_add_u64 v[244:245], s[0:1], 0, v[250:251]
	s_cbranch_vccnz .LBB0_420
.LBB0_419:
	v_mov_b32_e32 v246, v252
	v_ashrrev_i32_e32 v247, 31, v252
	v_lshlrev_b64 v[0:1], 7, v[246:247]
	v_lshl_add_u64 v[4:5], v[244:245], 0, v[0:1]
	global_load_dwordx4 v[0:3], v[4:5], off
	s_nop 0
	global_load_dwordx4 v[4:7], v[4:5], off offset:64
.LBB0_420:
	v_add_u32_e32 v26, 0x80, v252
	s_mov_b64 s[0:1], -1
	s_and_b64 vcc, exec, s[4:5]
	s_cbranch_vccz .LBB0_422
	v_min_i32_e32 v8, 0x81f, v26
	s_movk_i32 s0, 0x780
	v_add_u32_e32 v10, 0xfffff800, v8
	v_ashrrev_i32_e32 v9, 31, v8
	v_cmp_gt_i32_e32 vcc, s0, v252
	s_nop 1
	v_cndmask_b32_e32 v9, 0, v9, vcc
	v_cndmask_b32_e32 v8, v10, v8, vcc
	v_cndmask_b32_e32 v11, v243, v241, vcc
	v_cndmask_b32_e32 v10, v242, v240, vcc
	v_lshlrev_b64 v[8:9], 8, v[8:9]
	v_lshl_add_u64 v[30:31], v[10:11], 0, v[8:9]
	global_load_dwordx4 v[8:11], v[30:31], off
	global_load_dwordx4 v[12:15], v[30:31], off offset:16
	global_load_dwordx4 v[34:37], v[30:31], off offset:128
	global_load_dwordx4 v[38:41], v[30:31], off offset:144
	s_waitcnt vmcnt(3)
	v_cvt_pk_bf16_f32 v8, v8, v9
	v_cvt_pk_bf16_f32 v9, v10, v11
	s_waitcnt vmcnt(2)
	v_cvt_pk_bf16_f32 v10, v12, v13
	v_cvt_pk_bf16_f32 v11, v14, v15
	s_waitcnt vmcnt(1)
	v_cvt_pk_bf16_f32 v12, v34, v35
	v_cvt_pk_bf16_f32 v13, v36, v37
	s_waitcnt vmcnt(0)
	v_cvt_pk_bf16_f32 v14, v38, v39
	v_cvt_pk_bf16_f32 v15, v40, v41
	s_cbranch_execz .LBB0_423
	s_branch .LBB0_424

; DEVI void topk_unit(const Params& p, const int u, unsigned char* smem) {
;     ...
;     __syncthreads();
;     ...
;     for (int c = 0; c < 2; ++c) {
;         if (8 * c < npair) {
;             const int ipe = (npair < 8 * c + 8) ? npair : (8 * c + 8);
; #pragma unroll 1
;             for (int ip = 8 * c; ip < ipe; ++ip) {
;                 if (ip + 1 < npair) { TK_LOADK(na0, na1, 2 * ip + 2); TK_LOADK(nb0, nb1, 2 * ip + 3); }
.LBB0_423:
	v_ashrrev_i32_e32 v27, 31, v26
	v_lshlrev_b64 v[8:9], 7, v[26:27]
	v_lshl_add_u64 v[12:13], v[244:245], 0, v[8:9]
	global_load_dwordx4 v[8:11], v[12:13], off
	s_nop 0
	global_load_dwordx4 v[12:15], v[12:13], off offset:64
.LBB0_424:
	s_add_i32 s0, s24, 0x7f
	s_ashr_i32 s0, s0, 7
	s_add_i32 s0, s0, 1
	s_ashr_i32 s8, s0, 1
	s_movk_i32 s0, 0x4020
	s_waitcnt vmcnt(1)
	v_mul_f32_e32 v162, 0x3e000000, v17
	v_mul_f32_e32 v164, 0x3e000000, v18
	v_mul_i32_i24_e32 v17, -12, v172
	v_mul_lo_u32 v18, v171, s0
	v_mul_f32_e32 v160, 0x3e000000, v16
	v_mul_u32_u24_e32 v16, 0x2010, v28
	v_add3_u32 v32, v24, v17, v18
	v_lshlrev_b32_e32 v17, 2, v175
	s_waitcnt vmcnt(0)
	v_mul_f32_e32 v152, 0x3e000000, v20
	v_mul_f32_e32 v154, 0x3e000000, v21
	v_mul_f32_e32 v156, 0x3e000000, v22
	v_mul_f32_e32 v158, 0x3e000000, v23
	v_mul_f32_e32 v166, 0x3e000000, v19
	v_mad_u32_u24 v169, v28, s33, 0
	v_and_b32_e32 v173, 48, v25
	s_mov_b32 s6, 0
	s_cmp_gt_i32 s8, 0
	v_add3_u32 v174, v16, v17, s92
	s_waitcnt lgkmcnt(0)
	s_barrier
	s_cbranch_scc0 .LBB0_451
	v_add_u32_e32 v34, 0x180, v252
	s_min_u32 s7, s8, 8
	v_mov_b32_e32 v167, v166
	v_mov_b32_e32 v165, v164
	v_mov_b32_e32 v163, v162
	v_mov_b32_e32 v161, v160
	v_mov_b32_e32 v159, v158
	v_mov_b32_e32 v157, v156
	v_mov_b32_e32 v155, v154
	v_mov_b32_e32 v153, v152
	s_mov_b32 s9, s24
	s_mov_b32 s10, s24
	s_mov_b32 s11, s24
	v_add3_u32 v36, v16, v17, s92
	v_mov_b32_e32 v37, v175
	s_branch .LBB0_427

; DEVI void topk_unit(const Params& p, const int u, unsigned char* smem) {
;     ...
;                 if (ip + 1 < npair) { TK_LOADK(na0, na1, 2 * ip + 2); TK_LOADK(nb0, nb1, 2 * ip + 3); }
;     ...
;                 ka0 = na0; ka1 = na1; kb0 = nb0; kb1 = nb1;
.LBB0_427:
	s_waitcnt vmcnt(0)
	ds_bpermute_b32 v30, v253, v2
	ds_bpermute_b32 v31, v253, v3
	ds_bpermute_b32 v26, v253, v6
	ds_bpermute_b32 v27, v253, v7
	ds_bpermute_b32 v22, v253, v10
	ds_bpermute_b32 v23, v253, v11
	ds_bpermute_b32 v18, v253, v14
	ds_bpermute_b32 v19, v253, v15
	s_waitcnt lgkmcnt(4)
	ds_bpermute_b32 v28, v253, v0
	ds_bpermute_b32 v29, v253, v1
	ds_bpermute_b32 v24, v253, v4
	ds_bpermute_b32 v25, v253, v5
	ds_bpermute_b32 v20, v253, v8
	ds_bpermute_b32 v21, v253, v9
	ds_bpermute_b32 v16, v253, v12
	ds_bpermute_b32 v17, v253, v13
	s_waitcnt lgkmcnt(0)
	s_add_i32 s6, s6, 1
	s_cmp_ge_i32 s6, s8
	s_cbranch_scc1 .LBB0_426
	v_add_u32_e32 v8, 0xffffff80, v34
	s_mov_b64 s[0:1], -1
	s_and_b64 vcc, exec, s[4:5]
	s_cbranch_vccz .LBB0_430
	v_min_i32_e32 v0, 0x81f, v8
	v_add_u32_e32 v2, 0xfffff800, v0
	v_ashrrev_i32_e32 v1, 31, v0
	v_cmp_gt_i32_e32 vcc, s96, v8
	s_nop 1
	v_cndmask_b32_e32 v1, 0, v1, vcc
	v_cndmask_b32_e32 v0, v2, v0, vcc
	v_cndmask_b32_e32 v3, v243, v241, vcc
	v_cndmask_b32_e32 v2, v242, v240, vcc
	v_lshlrev_b64 v[0:1], 8, v[0:1]
	v_lshl_add_u64 v[14:15], v[2:3], 0, v[0:1]
	global_load_dwordx4 v[0:3], v[14:15], off
	global_load_dwordx4 v[4:7], v[14:15], off offset:16
	global_load_dwordx4 v[10:13], v[14:15], off offset:128
	global_load_dwordx4 v[38:41], v[14:15], off offset:144
	s_waitcnt vmcnt(3)
	v_cvt_pk_bf16_f32 v0, v0, v1
	v_cvt_pk_bf16_f32 v1, v2, v3
	s_waitcnt vmcnt(2)
	v_cvt_pk_bf16_f32 v2, v4, v5
	v_cvt_pk_bf16_f32 v3, v6, v7
	s_waitcnt vmcnt(1)
	v_cvt_pk_bf16_f32 v4, v10, v11
	v_cvt_pk_bf16_f32 v5, v12, v13
	s_waitcnt vmcnt(0)
	v_cvt_pk_bf16_f32 v6, v38, v39
	v_cvt_pk_bf16_f32 v7, v40, v41
	s_cbranch_execnz .LBB0_432
	s_branch .LBB0_431

; DEVI void topk_unit(const Params& p, const int u, unsigned char* smem) {
;     ...
;                 if (ip + 1 < npair) { TK_LOADK(na0, na1, 2 * ip + 2); TK_LOADK(nb0, nb1, 2 * ip + 3); }
.LBB0_431:
	v_ashrrev_i32_e32 v9, 31, v8
	v_lshlrev_b64 v[0:1], 7, v[8:9]
	v_lshl_add_u64 v[4:5], v[244:245], 0, v[0:1]
	global_load_dwordx4 v[0:3], v[4:5], off
	s_nop 0
	global_load_dwordx4 v[4:7], v[4:5], off offset:64
.LBB0_432:
	s_mov_b64 s[0:1], -1
	s_and_b64 vcc, exec, s[4:5]
	s_cbranch_vccz .LBB0_434
	v_min_i32_e32 v8, 0x81f, v34
	v_add_u32_e32 v10, 0xfffff800, v8
	v_ashrrev_i32_e32 v9, 31, v8
	v_cmp_gt_i32_e32 vcc, s96, v34
	s_nop 1
	v_cndmask_b32_e32 v9, 0, v9, vcc
	v_cndmask_b32_e32 v8, v10, v8, vcc
	v_cndmask_b32_e32 v11, v243, v241, vcc
	v_cndmask_b32_e32 v10, v242, v240, vcc
	v_lshlrev_b64 v[8:9], 8, v[8:9]
	v_lshl_add_u64 v[42:43], v[10:11], 0, v[8:9]
	global_load_dwordx4 v[8:11], v[42:43], off
	global_load_dwordx4 v[12:15], v[42:43], off offset:16
	global_load_dwordx4 v[38:41], v[42:43], off offset:128
	s_nop 0
	global_load_dwordx4 v[42:45], v[42:43], off offset:144
	s_waitcnt vmcnt(3)
	v_cvt_pk_bf16_f32 v8, v8, v9
	v_cvt_pk_bf16_f32 v9, v10, v11
	s_waitcnt vmcnt(2)
	v_cvt_pk_bf16_f32 v10, v12, v13
	v_cvt_pk_bf16_f32 v11, v14, v15
	s_waitcnt vmcnt(1)
	v_cvt_pk_bf16_f32 v12, v38, v39
	v_cvt_pk_bf16_f32 v13, v40, v41
	s_waitcnt vmcnt(0)
	v_cvt_pk_bf16_f32 v14, v42, v43
	v_cvt_pk_bf16_f32 v15, v44, v45
	s_cbranch_execnz .LBB0_426
	s_branch .LBB0_435

; DEVI void topk_unit(const Params& p, const int u, unsigned char* smem) {
;     ...
;                 if (ip + 1 < npair) { TK_LOADK(na0, na1, 2 * ip + 2); TK_LOADK(nb0, nb1, 2 * ip + 3); }
.LBB0_435:
	v_ashrrev_i32_e32 v35, 31, v34
	v_lshlrev_b64 v[8:9], 7, v[34:35]
	v_lshl_add_u64 v[12:13], v[244:245], 0, v[8:9]
	global_load_dwordx4 v[8:11], v[12:13], off
	s_nop 0
	global_load_dwordx4 v[12:15], v[12:13], off offset:64
	s_branch .LBB0_426

; DEVI void topk_unit(const Params& p, const int u, unsigned char* smem) {
;     ...
;     for (int c = 0; c < 2; ++c) {
;         if (8 * c < npair) {
;             const int ipe = (npair < 8 * c + 8) ? npair : (8 * c + 8);
; #pragma unroll 1
;             for (int ip = 8 * c; ip < ipe; ++ip) {
;                 if (ip + 1 < npair) { TK_LOADK(na0, na1, 2 * ip + 2); TK_LOADK(nb0, nb1, 2 * ip + 3); }
;     ...
;         } else {
; #pragma unroll
;             for (int j = 0; j < 32; ++j) { keyA[32 * c + j] = 0u; keyB[32 * c + j] = 0u; }
.LBB0_452:
	s_cmp_gt_i32 s8, 8
	v_mov_b32_e32 v80, 0
	s_cselect_b64 s[52:53], -1, 0
	s_cmp_lt_i32 s8, 9
	v_mov_b32_e32 v81, 0
	v_mov_b32_e32 v78, 0
	v_mov_b32_e32 v79, 0
	v_mov_b32_e32 v76, 0
	v_mov_b32_e32 v77, 0
	v_mov_b32_e32 v72, 0
	v_mov_b32_e32 v73, 0
	v_mov_b32_e32 v74, 0
	v_mov_b32_e32 v75, 0
	v_mov_b32_e32 v68, 0
	v_mov_b32_e32 v69, 0
	v_mov_b32_e32 v70, 0
	v_mov_b32_e32 v71, 0
	v_mov_b32_e32 v30, 0
	v_mov_b32_e32 v31, 0
	v_mov_b32_e32 v66, 0
	v_mov_b32_e32 v67, 0
	v_mov_b32_e32 v26, 0
	v_mov_b32_e32 v27, 0
	v_mov_b32_e32 v28, 0
	v_mov_b32_e32 v29, 0
	v_mov_b32_e32 v22, 0
	v_mov_b32_e32 v23, 0
	v_mov_b32_e32 v24, 0
	v_mov_b32_e32 v25, 0
	v_mov_b32_e32 v18, 0
	v_mov_b32_e32 v19, 0
	v_mov_b32_e32 v20, 0
	v_mov_b32_e32 v21, 0
	v_mov_b32_e32 v16, 0
	v_mov_b32_e32 v17, 0
	v_mov_b32_e32 v144, 0
	v_mov_b32_e32 v145, 0
	v_mov_b32_e32 v142, 0
	v_mov_b32_e32 v143, 0
	v_mov_b32_e32 v140, 0
	v_mov_b32_e32 v141, 0
	v_mov_b32_e32 v138, 0
	v_mov_b32_e32 v139, 0
	v_mov_b32_e32 v136, 0
	v_mov_b32_e32 v137, 0
	v_mov_b32_e32 v128, 0
	v_mov_b32_e32 v129, 0
	v_mov_b32_e32 v134, 0
	v_mov_b32_e32 v135, 0
	v_mov_b32_e32 v132, 0
	v_mov_b32_e32 v133, 0
	v_mov_b32_e32 v130, 0
	v_mov_b32_e32 v131, 0
	v_mov_b32_e32 v120, 0
	v_mov_b32_e32 v121, 0
	v_mov_b32_e32 v126, 0
	v_mov_b32_e32 v127, 0
	v_mov_b32_e32 v124, 0
	v_mov_b32_e32 v125, 0
	v_mov_b32_e32 v122, 0
	v_mov_b32_e32 v123, 0
	v_mov_b32_e32 v114, 0
	v_mov_b32_e32 v115, 0
	v_mov_b32_e32 v118, 0
	v_mov_b32_e32 v119, 0
	v_mov_b32_e32 v116, 0
	v_mov_b32_e32 v117, 0
	s_cbranch_scc1 .LBB0_479
	s_waitcnt vmcnt(1)
	v_mov_b64_e32 v[18:19], v[2:3]
	s_waitcnt vmcnt(0)
	v_mov_b64_e32 v[22:23], v[6:7]
	v_mov_b64_e32 v[26:27], v[10:11]
	v_mov_b64_e32 v[30:31], v[14:15]
	s_min_u32 s9, s8, 16
	v_mov_b32_e32 v167, v166
	v_mov_b32_e32 v165, v164
	v_mov_b32_e32 v163, v162
	v_mov_b32_e32 v161, v160
	v_mov_b32_e32 v159, v158
	v_mov_b32_e32 v157, v156
	v_mov_b32_e32 v155, v154
	v_mov_b32_e32 v153, v152
	s_mov_b32 s10, s24
	s_mov_b32 s11, s24
	s_mov_b32 s12, s24
	v_add_u32_e32 v66, 0x980, v168
	v_add_u32_e32 v68, 0x800, v175
	s_mov_b32 s13, 8
	s_waitcnt vmcnt(0)
	ds_bpermute_b32 v0, v253, v0
	ds_bpermute_b32 v1, v253, v1
	ds_bpermute_b32 v2, v253, v2
	ds_bpermute_b32 v3, v253, v3
	ds_bpermute_b32 v4, v253, v4
	ds_bpermute_b32 v5, v253, v5
	ds_bpermute_b32 v6, v253, v6
	ds_bpermute_b32 v7, v253, v7
	s_waitcnt lgkmcnt(0)
	ds_bpermute_b32 v8, v253, v8
	ds_bpermute_b32 v9, v253, v9
	ds_bpermute_b32 v10, v253, v10
	ds_bpermute_b32 v11, v253, v11
	ds_bpermute_b32 v12, v253, v12
	ds_bpermute_b32 v13, v253, v13
	ds_bpermute_b32 v14, v253, v14
	ds_bpermute_b32 v15, v253, v15
	s_waitcnt lgkmcnt(0)
	v_mov_b64_e32 v[16:17], v[0:1]
	v_mov_b64_e32 v[20:21], v[4:5]
	v_mov_b64_e32 v[24:25], v[8:9]
	v_mov_b64_e32 v[28:29], v[12:13]
	s_branch .LBB0_455
